# in-proj, down-proj and out-proj GEMM main loops: LDS-DMA addresses in scalar-base form (SALU adds) instead of sixteen 64-bit VALU adds per iteration
# speedup vs baseline: 1.0117x; 1.0003x over previous
; #define PG8_STAGE(bufoff, gbase, voff) do { _Pragma("unroll") for (int _i = 0; _i < 2; ++_i) \
;         __builtin_amdgcn_global_load_lds((const unsigned*)((const char*)(gbase) + (voff)[_i]), (LAS unsigned*)(lds + (bufoff) + ldsw + _i * 8192), 16, 0, 0); } while (0)
; #define PG8_LDA(dst, b, h) do { _Pragma("unroll") for (int m = 0; m < 4; ++m) _Pragma("unroll") for (int k = 0; k < 2; ++k) dst[m][k] = *(const LAS bf16x8*)(lds + PG8_SA(b, h) + aoff + m * 2048 + k * 1024); } while (0)
; #define PG8_LDB(dst, b, h) do { _Pragma("unroll") for (int n = 0; n < 2; ++n) _Pragma("unroll") for (int k = 0; k < 2; ++k) dst[n][k] = *(const LAS bf16x8*)(lds + PG8_SB(b, h) + boff + n * 2048 + k * 1024); } while (0)
; #define PG8_MMA(ai, bj, At, Bt) do { __builtin_amdgcn_s_setprio(1); _Pragma("unroll") for (int m = 0; m < 4; ++m) _Pragma("unroll") for (int n = 0; n < 2; ++n) _Pragma("unroll") for (int k = 0; k < 2; ++k) \
;         acc[ai][bj][m][n] = __builtin_amdgcn_mfma_f32_16x16x32_bf16(Bt[n][k], At[m][k], acc[ai][bj][m][n], 0, 0, 0); __builtin_amdgcn_s_setprio(0); } while (0)
; #define PG8_WAIT_V(n) asm volatile("s_waitcnt vmcnt(" #n ")" ::: "memory")
; #define PG8_WAIT_L(n) asm volatile("s_waitcnt lgkmcnt(" #n ")" ::: "memory")
; #define PG8_BAR __builtin_amdgcn_s_barrier()
; #define PG8_SCHED __builtin_amdgcn_sched_barrier(0)
; template <class Epi, class Sched, bool ALIGN_EPI>
; DI void gemm_phase(LAS unsigned char* lds, const Gemm g, const Sched& S, const Epi& E) {
;     ...
;         for (int t = 0; t < nt; t += 2) {
;             const bool last = (t == nt - 2);
;             const char* a1 = cA + (size_t)(t + 1) * kstep;
;             const char* a2 = last ? nA : cA + (size_t)(t + 2) * kstep; const char* b2 = last ? nB : cB + (size_t)(t + 2) * kstep;
;             const char* a3 = a2 + kstep; const char* b3 = b2 + kstep;
;             PG8_LDB(B0, 0, 0); PG8_LDB(B1, 0, 1); PG8_SCHED; PG8_LDA(At, 0, 0); PG8_STAGE(PG8_SA(1, 1), a1 + hstep, voffA);
;             PG8_WAIT_V(8); PG8_WAIT_L(0); PG8_BAR; PG8_MMA(0, 0, At, B0); PG8_MMA(0, 1, At, B1); PG8_BAR; PG8_SCHED;
;             PG8_LDA(At, 0, 1); PG8_STAGE(PG8_SB(0, 0), b2, voffA); PG8_STAGE(PG8_SB(0, 1), b2 + hstep, voffA); PG8_STAGE(PG8_SA(0, 0), a2, voffA);
;             PG8_WAIT_V(8); PG8_WAIT_L(0); PG8_BAR; PG8_MMA(1, 0, At, B0); PG8_MMA(1, 1, At, B1); PG8_BAR; PG8_SCHED;
.LBB0_104:
	ds_read_b128 v[48:51], v196
	ds_read_b128 v[52:55], v196 offset:1024
	ds_read_b128 v[56:59], v196 offset:2048
	ds_read_b128 v[60:63], v196 offset:3072
	ds_read_b128 v[182:185], v197
	ds_read_b128 v[186:189], v197 offset:1024
	ds_read_b128 v[200:203], v197 offset:2048
	ds_read_b128 v[204:207], v197 offset:3072
	s_add_u32 s8, s0, 0xfffc0080
	s_addc_u32 s9, s1, -1
	s_cmp_eq_u32 s47, 12
	s_cselect_b32 s45, s7, s9
	s_cselect_b32 s44, s11, s8
	s_cselect_b32 s9, s18, s46
	s_cselect_b32 s8, s29, s31
	s_add_i32 m0, s64, 0xc000
	ds_read_b128 v[208:211], v194
	ds_read_b128 v[212:215], v194 offset:1024
	ds_read_b128 v[216:219], v194 offset:2048
	ds_read_b128 v[220:223], v194 offset:3072
	ds_read_b128 v[228:231], v194 offset:4096
	ds_read_b128 v[232:235], v194 offset:5120
	ds_read_b128 v[236:239], v194 offset:6144
	ds_read_b128 v[240:243], v194 offset:7168
	global_load_lds_dwordx4 v174, s[0:1]
	s_add_i32 m0, s64, 0xe000
	s_nop 0
	global_load_lds_dwordx4 v176, s[0:1]
	s_waitcnt vmcnt(8)
	s_waitcnt lgkmcnt(0)
	s_barrier
	s_setprio 1
	s_waitcnt lgkmcnt(0)
	v_mfma_f32_16x16x32_bf16 v[140:143], v[48:51], v[208:211], v[140:143]
	v_mfma_f32_16x16x32_bf16 v[136:139], v[56:59], v[208:211], v[136:139]
	v_mfma_f32_16x16x32_bf16 v[124:127], v[48:51], v[216:219], v[124:127]
	v_mfma_f32_16x16x32_bf16 v[120:123], v[56:59], v[216:219], v[120:123]
	v_mfma_f32_16x16x32_bf16 v[108:111], v[48:51], v[228:231], v[108:111]
	v_mfma_f32_16x16x32_bf16 v[104:107], v[56:59], v[228:231], v[104:107]
	v_mfma_f32_16x16x32_bf16 v[92:95], v[48:51], v[236:239], v[92:95]
	v_mfma_f32_16x16x32_bf16 v[88:91], v[56:59], v[236:239], v[88:91]
	v_mfma_f32_16x16x32_bf16 v[140:143], v[52:55], v[212:215], v[140:143]
	v_mfma_f32_16x16x32_bf16 v[136:139], v[60:63], v[212:215], v[136:139]
	v_mfma_f32_16x16x32_bf16 v[124:127], v[52:55], v[220:223], v[124:127]
	v_mfma_f32_16x16x32_bf16 v[120:123], v[60:63], v[220:223], v[120:123]
	v_mfma_f32_16x16x32_bf16 v[108:111], v[52:55], v[232:235], v[108:111]
	v_mfma_f32_16x16x32_bf16 v[104:107], v[60:63], v[232:235], v[104:107]
	v_mfma_f32_16x16x32_bf16 v[92:95], v[52:55], v[240:243], v[92:95]
	v_mfma_f32_16x16x32_bf16 v[88:91], v[60:63], v[240:243], v[88:91]
	s_setprio 0
	s_setprio 1
	v_mfma_f32_16x16x32_bf16 v[132:135], v[182:185], v[208:211], v[132:135]
	v_mfma_f32_16x16x32_bf16 v[128:131], v[200:203], v[208:211], v[128:131]
	v_mfma_f32_16x16x32_bf16 v[116:119], v[182:185], v[216:219], v[116:119]
	v_mfma_f32_16x16x32_bf16 v[112:115], v[200:203], v[216:219], v[112:115]
	v_mfma_f32_16x16x32_bf16 v[100:103], v[182:185], v[228:231], v[100:103]
	v_mfma_f32_16x16x32_bf16 v[96:99], v[200:203], v[228:231], v[96:99]
	v_mfma_f32_16x16x32_bf16 v[84:87], v[182:185], v[236:239], v[84:87]
	v_mfma_f32_16x16x32_bf16 v[80:83], v[200:203], v[236:239], v[80:83]
	v_mfma_f32_16x16x32_bf16 v[132:135], v[186:189], v[212:215], v[132:135]
	v_mfma_f32_16x16x32_bf16 v[128:131], v[204:207], v[212:215], v[128:131]
	v_mfma_f32_16x16x32_bf16 v[116:119], v[186:189], v[220:223], v[116:119]
	v_mfma_f32_16x16x32_bf16 v[112:115], v[204:207], v[220:223], v[112:115]
	v_mfma_f32_16x16x32_bf16 v[100:103], v[186:189], v[232:235], v[100:103]
	v_mfma_f32_16x16x32_bf16 v[96:99], v[204:207], v[232:235], v[96:99]
	v_mfma_f32_16x16x32_bf16 v[84:87], v[186:189], v[240:243], v[84:87]
	v_mfma_f32_16x16x32_bf16 v[80:83], v[204:207], v[240:243], v[80:83]
	s_setprio 0
	s_barrier
	s_add_i32 s48, s75, s63
	s_add_u32 s94, s8, s22
	s_addc_u32 s95, s9, s23
	s_add_u32 s96, s44, s22
	s_addc_u32 s97, s45, s23
	s_mov_b32 m0, s48
	ds_read_b128 v[208:211], v194 offset:16384
	ds_read_b128 v[212:215], v194 offset:17408
	ds_read_b128 v[216:219], v194 offset:18432
	ds_read_b128 v[220:223], v194 offset:19456
	ds_read_b128 v[228:231], v194 offset:20480
	ds_read_b128 v[232:235], v194 offset:21504
	ds_read_b128 v[236:239], v194 offset:22528
	ds_read_b128 v[240:243], v194 offset:23552
	global_load_lds_dwordx4 v146, s[8:9]
	s_add_i32 m0, s48, 0x2000
	s_add_u32 s48, s8, 0x40000
	s_addc_u32 s49, s9, 0
	s_add_i32 s50, s76, s63
	global_load_lds_dwordx4 v148, s[8:9]
	s_mov_b32 m0, s50
	s_nop 0
	global_load_lds_dwordx4 v146, s[48:49]
	s_add_i32 m0, s50, 0x2000
	s_nop 0
	global_load_lds_dwordx4 v148, s[48:49]
	s_mov_b32 m0, s64
	s_nop 0
	global_load_lds_dwordx4 v146, s[44:45]
	s_mov_b32 m0, s65
	s_nop 0
	global_load_lds_dwordx4 v148, s[44:45]
	s_waitcnt vmcnt(8)
	s_waitcnt lgkmcnt(0)
	s_barrier
	s_setprio 1
	s_waitcnt lgkmcnt(0)
	v_mfma_f32_16x16x32_bf16 v[76:79], v[48:51], v[208:211], v[76:79]
	v_mfma_f32_16x16x32_bf16 v[72:75], v[56:59], v[208:211], v[72:75]
	v_mfma_f32_16x16x32_bf16 v[44:47], v[48:51], v[216:219], v[44:47]
	v_mfma_f32_16x16x32_bf16 v[40:43], v[56:59], v[216:219], v[40:43]
	v_mfma_f32_16x16x32_bf16 v[28:31], v[48:51], v[228:231], v[28:31]
	v_mfma_f32_16x16x32_bf16 v[24:27], v[56:59], v[228:231], v[24:27]
	v_mfma_f32_16x16x32_bf16 v[12:15], v[48:51], v[236:239], v[12:15]
	v_mfma_f32_16x16x32_bf16 v[8:11], v[56:59], v[236:239], v[8:11]
	v_mfma_f32_16x16x32_bf16 v[76:79], v[52:55], v[212:215], v[76:79]
	v_mfma_f32_16x16x32_bf16 v[72:75], v[60:63], v[212:215], v[72:75]
	v_mfma_f32_16x16x32_bf16 v[44:47], v[52:55], v[220:223], v[44:47]
	v_mfma_f32_16x16x32_bf16 v[40:43], v[60:63], v[220:223], v[40:43]
	v_mfma_f32_16x16x32_bf16 v[28:31], v[52:55], v[232:235], v[28:31]
	v_mfma_f32_16x16x32_bf16 v[24:27], v[60:63], v[232:235], v[24:27]
	v_mfma_f32_16x16x32_bf16 v[12:15], v[52:55], v[240:243], v[12:15]
	v_mfma_f32_16x16x32_bf16 v[8:11], v[60:63], v[240:243], v[8:11]
	s_setprio 0
	s_setprio 1
	v_mfma_f32_16x16x32_bf16 v[36:39], v[182:185], v[216:219], v[36:39]
	v_mfma_f32_16x16x32_bf16 v[32:35], v[200:203], v[216:219], v[32:35]
	v_mfma_f32_16x16x32_bf16 v[20:23], v[182:185], v[228:231], v[20:23]
	v_mfma_f32_16x16x32_bf16 v[16:19], v[200:203], v[228:231], v[16:19]
	v_mfma_f32_16x16x32_bf16 v[4:7], v[182:185], v[236:239], v[4:7]
	v_mfma_f32_16x16x32_bf16 v[0:3], v[200:203], v[236:239], v[0:3]
	v_mfma_f32_16x16x32_bf16 v[48:51], v[182:185], v[208:211], v[68:71]
	v_mfma_f32_16x16x32_bf16 v[52:55], v[200:203], v[208:211], v[64:67]
	v_mfma_f32_16x16x32_bf16 v[36:39], v[186:189], v[220:223], v[36:39]
	v_mfma_f32_16x16x32_bf16 v[32:35], v[204:207], v[220:223], v[32:35]
	v_mfma_f32_16x16x32_bf16 v[20:23], v[186:189], v[232:235], v[20:23]
	v_mfma_f32_16x16x32_bf16 v[16:19], v[204:207], v[232:235], v[16:19]
	v_mfma_f32_16x16x32_bf16 v[4:7], v[186:189], v[240:243], v[4:7]
	v_mfma_f32_16x16x32_bf16 v[0:3], v[204:207], v[240:243], v[0:3]
	v_mfma_f32_16x16x32_bf16 v[48:51], v[186:189], v[212:215], v[48:51]
	v_mfma_f32_16x16x32_bf16 v[52:55], v[204:207], v[212:215], v[52:55]
	s_setprio 0
	s_barrier
; #define PG8_STAGE(bufoff, gbase, voff) do { _Pragma("unroll") for (int _i = 0; _i < 2; ++_i) \
;         __builtin_amdgcn_global_load_lds((const unsigned*)((const char*)(gbase) + (voff)[_i]), (LAS unsigned*)(lds + (bufoff) + ldsw + _i * 8192), 16, 0, 0); } while (0)
; #define PG8_LDA(dst, b, h) do { _Pragma("unroll") for (int m = 0; m < 4; ++m) _Pragma("unroll") for (int k = 0; k < 2; ++k) dst[m][k] = *(const LAS bf16x8*)(lds + PG8_SA(b, h) + aoff + m * 2048 + k * 1024); } while (0)
; #define PG8_LDB(dst, b, h) do { _Pragma("unroll") for (int n = 0; n < 2; ++n) _Pragma("unroll") for (int k = 0; k < 2; ++k) dst[n][k] = *(const LAS bf16x8*)(lds + PG8_SB(b, h) + boff + n * 2048 + k * 1024); } while (0)
; #define PG8_MMA(ai, bj, At, Bt) do { __builtin_amdgcn_s_setprio(1); _Pragma("unroll") for (int m = 0; m < 4; ++m) _Pragma("unroll") for (int n = 0; n < 2; ++n) _Pragma("unroll") for (int k = 0; k < 2; ++k) \
;         acc[ai][bj][m][n] = __builtin_amdgcn_mfma_f32_16x16x32_bf16(Bt[n][k], At[m][k], acc[ai][bj][m][n], 0, 0, 0); __builtin_amdgcn_s_setprio(0); } while (0)
; #define PG8_WAIT_V(n) asm volatile("s_waitcnt vmcnt(" #n ")" ::: "memory")
; #define PG8_WAIT_L(n) asm volatile("s_waitcnt lgkmcnt(" #n ")" ::: "memory")
; #define PG8_BAR __builtin_amdgcn_s_barrier()
; #define PG8_SCHED __builtin_amdgcn_sched_barrier(0)
; template <class Epi, class Sched, bool ALIGN_EPI>
; DI void gemm_phase(LAS unsigned char* lds, const Gemm g, const Sched& S, const Epi& E) {
;     ...
;             PG8_LDB(B0, 1, 0); PG8_LDB(B1, 1, 1); PG8_SCHED; PG8_LDA(At, 1, 0); PG8_STAGE(PG8_SA(0, 1), a2 + hstep, voffA);
;             PG8_WAIT_V(8); PG8_WAIT_L(0); PG8_BAR; PG8_MMA(0, 0, At, B0); PG8_MMA(0, 1, At, B1); PG8_BAR; PG8_SCHED;
;             PG8_LDA(At, 1, 1); PG8_STAGE(PG8_SB(1, 0), b3, voffA); PG8_STAGE(PG8_SB(1, 1), b3 + hstep, voffA); PG8_STAGE(PG8_SA(1, 0), a3, voffA);
;             PG8_WAIT_V(8); PG8_WAIT_L(0); PG8_BAR; PG8_MMA(1, 0, At, B0); PG8_MMA(1, 1, At, B1); PG8_BAR; PG8_SCHED;
;         }
	s_add_i32 s48, 0, 0x18000
	s_add_i32 s49, 0, 0x1c000
	v_add_u32_e32 v68, s48, v157
	v_add_u32_e32 v150, s49, v157
	ds_read_b128 v[56:59], v68
	ds_read_b128 v[60:63], v68 offset:1024
	ds_read_b128 v[64:67], v68 offset:2048
	ds_read_b128 v[68:71], v68 offset:3072
	ds_read_b128 v[182:185], v150
	ds_read_b128 v[186:189], v150 offset:1024
	ds_read_b128 v[200:203], v150 offset:2048
	ds_read_b128 v[204:207], v150 offset:3072
	s_add_u32 s44, s44, 0x40000
	s_addc_u32 s45, s45, 0
	s_mov_b32 m0, s66
	ds_read_b128 v[208:211], v194 offset:32768
	ds_read_b128 v[212:215], v194 offset:33792
	ds_read_b128 v[216:219], v194 offset:34816
	ds_read_b128 v[220:223], v194 offset:35840
	ds_read_b128 v[228:231], v194 offset:36864
	ds_read_b128 v[232:235], v194 offset:37888
	ds_read_b128 v[236:239], v194 offset:38912
	ds_read_b128 v[240:243], v194 offset:39936
	global_load_lds_dwordx4 v146, s[44:45]
	s_mov_b32 m0, s67
	s_nop 0
	global_load_lds_dwordx4 v148, s[44:45]
	s_waitcnt vmcnt(8)
	s_waitcnt lgkmcnt(0)
	s_barrier
	s_setprio 1
	s_waitcnt lgkmcnt(0)
	v_mfma_f32_16x16x32_bf16 v[140:143], v[56:59], v[208:211], v[140:143]
	v_mfma_f32_16x16x32_bf16 v[136:139], v[64:67], v[208:211], v[136:139]
	v_mfma_f32_16x16x32_bf16 v[124:127], v[56:59], v[216:219], v[124:127]
	v_mfma_f32_16x16x32_bf16 v[120:123], v[64:67], v[216:219], v[120:123]
	v_mfma_f32_16x16x32_bf16 v[108:111], v[56:59], v[228:231], v[108:111]
	v_mfma_f32_16x16x32_bf16 v[104:107], v[64:67], v[228:231], v[104:107]
	v_mfma_f32_16x16x32_bf16 v[92:95], v[56:59], v[236:239], v[92:95]
	v_mfma_f32_16x16x32_bf16 v[88:91], v[64:67], v[236:239], v[88:91]
	v_mfma_f32_16x16x32_bf16 v[140:143], v[60:63], v[212:215], v[140:143]
	v_mfma_f32_16x16x32_bf16 v[136:139], v[68:71], v[212:215], v[136:139]
	v_mfma_f32_16x16x32_bf16 v[124:127], v[60:63], v[220:223], v[124:127]
	v_mfma_f32_16x16x32_bf16 v[120:123], v[68:71], v[220:223], v[120:123]
	v_mfma_f32_16x16x32_bf16 v[108:111], v[60:63], v[232:235], v[108:111]
	v_mfma_f32_16x16x32_bf16 v[104:107], v[68:71], v[232:235], v[104:107]
	v_mfma_f32_16x16x32_bf16 v[92:95], v[60:63], v[240:243], v[92:95]
	v_mfma_f32_16x16x32_bf16 v[88:91], v[68:71], v[240:243], v[88:91]
	s_setprio 0
	s_setprio 1
	v_mfma_f32_16x16x32_bf16 v[132:135], v[182:185], v[208:211], v[132:135]
	v_mfma_f32_16x16x32_bf16 v[128:131], v[200:203], v[208:211], v[128:131]
	v_mfma_f32_16x16x32_bf16 v[116:119], v[182:185], v[216:219], v[116:119]
	v_mfma_f32_16x16x32_bf16 v[112:115], v[200:203], v[216:219], v[112:115]
	v_mfma_f32_16x16x32_bf16 v[100:103], v[182:185], v[228:231], v[100:103]
	v_mfma_f32_16x16x32_bf16 v[96:99], v[200:203], v[228:231], v[96:99]
	v_mfma_f32_16x16x32_bf16 v[84:87], v[182:185], v[236:239], v[84:87]
	v_mfma_f32_16x16x32_bf16 v[80:83], v[200:203], v[236:239], v[80:83]
	v_mfma_f32_16x16x32_bf16 v[132:135], v[186:189], v[212:215], v[132:135]
	v_mfma_f32_16x16x32_bf16 v[128:131], v[204:207], v[212:215], v[128:131]
	v_mfma_f32_16x16x32_bf16 v[116:119], v[186:189], v[220:223], v[116:119]
	v_mfma_f32_16x16x32_bf16 v[112:115], v[204:207], v[220:223], v[112:115]
	v_mfma_f32_16x16x32_bf16 v[100:103], v[186:189], v[232:235], v[100:103]
	v_mfma_f32_16x16x32_bf16 v[96:99], v[204:207], v[232:235], v[96:99]
	v_mfma_f32_16x16x32_bf16 v[84:87], v[186:189], v[240:243], v[84:87]
	v_mfma_f32_16x16x32_bf16 v[80:83], v[204:207], v[240:243], v[80:83]
	s_setprio 0
	s_barrier
	s_add_i32 s44, s48, s63
	s_mov_b32 m0, s44
	ds_read_b128 v[208:211], v194 offset:49152
	ds_read_b128 v[212:215], v194 offset:50176
	ds_read_b128 v[216:219], v194 offset:51200
	ds_read_b128 v[220:223], v194 offset:52224
	ds_read_b128 v[228:231], v194 offset:53248
	ds_read_b128 v[232:235], v194 offset:54272
	ds_read_b128 v[236:239], v194 offset:55296
	ds_read_b128 v[240:243], v194 offset:56320
	global_load_lds_dwordx4 v146, s[94:95]
	s_add_i32 m0, s44, 0x2000
	s_add_u32 s8, s8, 0x40080
	s_addc_u32 s9, s9, 0
	s_add_i32 s44, s49, s63
	global_load_lds_dwordx4 v148, s[94:95]
	s_mov_b32 m0, s44
	s_nop 0
	global_load_lds_dwordx4 v146, s[8:9]
	s_add_i32 m0, s44, 0x2000
	s_nop 0
	global_load_lds_dwordx4 v148, s[8:9]
	s_mov_b32 m0, s70
	s_nop 0
	global_load_lds_dwordx4 v146, s[96:97]
	s_mov_b32 m0, s71
	s_nop 0
	global_load_lds_dwordx4 v148, s[96:97]
	s_waitcnt vmcnt(8)
	s_waitcnt lgkmcnt(0)
	s_barrier
	s_setprio 1
	s_waitcnt lgkmcnt(0)
	v_mfma_f32_16x16x32_bf16 v[76:79], v[56:59], v[208:211], v[76:79]
	v_mfma_f32_16x16x32_bf16 v[72:75], v[64:67], v[208:211], v[72:75]
	v_mfma_f32_16x16x32_bf16 v[44:47], v[56:59], v[216:219], v[44:47]
	v_mfma_f32_16x16x32_bf16 v[40:43], v[64:67], v[216:219], v[40:43]
	v_mfma_f32_16x16x32_bf16 v[28:31], v[56:59], v[228:231], v[28:31]
	v_mfma_f32_16x16x32_bf16 v[24:27], v[64:67], v[228:231], v[24:27]
	v_mfma_f32_16x16x32_bf16 v[12:15], v[56:59], v[236:239], v[12:15]
	v_mfma_f32_16x16x32_bf16 v[8:11], v[64:67], v[236:239], v[8:11]
	v_mfma_f32_16x16x32_bf16 v[76:79], v[60:63], v[212:215], v[76:79]
	v_mfma_f32_16x16x32_bf16 v[72:75], v[68:71], v[212:215], v[72:75]
	v_mfma_f32_16x16x32_bf16 v[44:47], v[60:63], v[220:223], v[44:47]
	v_mfma_f32_16x16x32_bf16 v[40:43], v[68:71], v[220:223], v[40:43]
	v_mfma_f32_16x16x32_bf16 v[28:31], v[60:63], v[232:235], v[28:31]
	v_mfma_f32_16x16x32_bf16 v[24:27], v[68:71], v[232:235], v[24:27]
	v_mfma_f32_16x16x32_bf16 v[12:15], v[60:63], v[240:243], v[12:15]
	v_mfma_f32_16x16x32_bf16 v[8:11], v[68:71], v[240:243], v[8:11]
	s_setprio 0
	s_setprio 1
	v_mfma_f32_16x16x32_bf16 v[48:51], v[182:185], v[208:211], v[48:51]
	v_mfma_f32_16x16x32_bf16 v[68:71], v[186:189], v[212:215], v[48:51]
	v_mfma_f32_16x16x32_bf16 v[48:51], v[200:203], v[208:211], v[52:55]
	v_mfma_f32_16x16x32_bf16 v[36:39], v[182:185], v[216:219], v[36:39]
	v_mfma_f32_16x16x32_bf16 v[32:35], v[200:203], v[216:219], v[32:35]
	v_mfma_f32_16x16x32_bf16 v[20:23], v[182:185], v[228:231], v[20:23]
	v_mfma_f32_16x16x32_bf16 v[16:19], v[200:203], v[228:231], v[16:19]
	v_mfma_f32_16x16x32_bf16 v[4:7], v[182:185], v[236:239], v[4:7]
	v_mfma_f32_16x16x32_bf16 v[0:3], v[200:203], v[236:239], v[0:3]
	v_mfma_f32_16x16x32_bf16 v[64:67], v[204:207], v[212:215], v[48:51]
	v_mfma_f32_16x16x32_bf16 v[36:39], v[186:189], v[220:223], v[36:39]
	v_mfma_f32_16x16x32_bf16 v[32:35], v[204:207], v[220:223], v[32:35]
	v_mfma_f32_16x16x32_bf16 v[20:23], v[186:189], v[232:235], v[20:23]
	v_mfma_f32_16x16x32_bf16 v[16:19], v[204:207], v[232:235], v[16:19]
	v_mfma_f32_16x16x32_bf16 v[4:7], v[186:189], v[240:243], v[4:7]
	v_mfma_f32_16x16x32_bf16 v[0:3], v[204:207], v[240:243], v[0:3]
	s_setprio 0
	s_barrier
	s_add_i32 s47, s47, 2
	s_add_u32 s0, s0, 0x100
	s_addc_u32 s1, s1, 0
	s_add_u32 s31, s31, 0x100
	s_addc_u32 s46, s46, 0
	s_cmp_gt_u32 s47, 13
	s_cbranch_scc0 .LBB0_104
	s_and_b64 vcc, exec, s[24:25]
	s_cbranch_vccz .LBB0_107
	s_barrier

; #define PG8_STAGE(bufoff, gbase, voff) do { _Pragma("unroll") for (int _i = 0; _i < 2; ++_i) \
;         __builtin_amdgcn_global_load_lds((const unsigned*)((const char*)(gbase) + (voff)[_i]), (LAS unsigned*)(lds + (bufoff) + ldsw + _i * 8192), 16, 0, 0); } while (0)
; #define PG8_LDA(dst, b, h) do { _Pragma("unroll") for (int m = 0; m < 4; ++m) _Pragma("unroll") for (int k = 0; k < 2; ++k) dst[m][k] = *(const LAS bf16x8*)(lds + PG8_SA(b, h) + aoff + m * 2048 + k * 1024); } while (0)
; #define PG8_LDB(dst, b, h) do { _Pragma("unroll") for (int n = 0; n < 2; ++n) _Pragma("unroll") for (int k = 0; k < 2; ++k) dst[n][k] = *(const LAS bf16x8*)(lds + PG8_SB(b, h) + boff + n * 2048 + k * 1024); } while (0)
; #define PG8_MMA(ai, bj, At, Bt) do { __builtin_amdgcn_s_setprio(1); _Pragma("unroll") for (int m = 0; m < 4; ++m) _Pragma("unroll") for (int n = 0; n < 2; ++n) _Pragma("unroll") for (int k = 0; k < 2; ++k) \
;         acc[ai][bj][m][n] = __builtin_amdgcn_mfma_f32_16x16x32_bf16(Bt[n][k], At[m][k], acc[ai][bj][m][n], 0, 0, 0); __builtin_amdgcn_s_setprio(0); } while (0)
; #define PG8_WAIT_V(n) asm volatile("s_waitcnt vmcnt(" #n ")" ::: "memory")
; #define PG8_WAIT_L(n) asm volatile("s_waitcnt lgkmcnt(" #n ")" ::: "memory")
; #define PG8_BAR __builtin_amdgcn_s_barrier()
; #define PG8_SCHED __builtin_amdgcn_sched_barrier(0)
; template <class Epi, class Sched, bool ALIGN_EPI>
; DI void gemm_phase(LAS unsigned char* lds, const Gemm g, const Sched& S, const Epi& E) {
;     ...
;         for (int t = 0; t < nt; t += 2) {
;             const bool last = (t == nt - 2);
;             const char* a1 = cA + (size_t)(t + 1) * kstep;
;             const char* a2 = last ? nA : cA + (size_t)(t + 2) * kstep; const char* b2 = last ? nB : cB + (size_t)(t + 2) * kstep;
;             const char* a3 = a2 + kstep; const char* b3 = b2 + kstep;
;             PG8_LDB(B0, 0, 0); PG8_LDB(B1, 0, 1); PG8_SCHED; PG8_LDA(At, 0, 0); PG8_STAGE(PG8_SA(1, 1), a1 + hstep, voffA);
;             PG8_WAIT_V(8); PG8_WAIT_L(0); PG8_BAR; PG8_MMA(0, 0, At, B0); PG8_MMA(0, 1, At, B1); PG8_BAR; PG8_SCHED;
;             PG8_LDA(At, 0, 1); PG8_STAGE(PG8_SB(0, 0), b2, voffA); PG8_STAGE(PG8_SB(0, 1), b2 + hstep, voffA); PG8_STAGE(PG8_SA(0, 0), a2, voffA);
;             PG8_WAIT_V(8); PG8_WAIT_L(0); PG8_BAR; PG8_MMA(1, 0, At, B0); PG8_MMA(1, 1, At, B1); PG8_BAR; PG8_SCHED;
.LBB0_791:
	s_add_u32 s16, s0, 0xfff50080
	s_addc_u32 s17, s1, -1
	s_add_i32 s42, 0, 0x10000
	s_cmp_eq_u32 s37, 40
	s_cselect_b32 s19, s13, s17
	s_cselect_b32 s18, s12, s16
	s_cselect_b32 s17, s5, s36
	s_cselect_b32 s16, s4, s35
	s_add_i32 s44, 0, 0x14000
	v_add_u32_e32 v140, s42, v165
	v_add_u32_e32 v156, s44, v165
	ds_read_b128 v[128:131], v140
	ds_read_b128 v[132:135], v140 offset:1024
	ds_read_b128 v[136:139], v140 offset:2048
	ds_read_b128 v[140:143], v140 offset:3072
	ds_read_b128 v[144:147], v156
	ds_read_b128 v[148:151], v156 offset:1024
	ds_read_b128 v[152:155], v156 offset:2048
	ds_read_b128 v[156:159], v156 offset:3072
	s_add_i32 m0, s23, 0xc000
	ds_read_b128 v[160:163], v167
	ds_read_b128 v[182:185], v167 offset:1024
	ds_read_b128 v[186:189], v167 offset:2048
	ds_read_b128 v[190:193], v167 offset:3072
	ds_read_b128 v[194:197], v167 offset:4096
	ds_read_b128 v[198:201], v167 offset:5120
	ds_read_b128 v[202:205], v167 offset:6144
	ds_read_b128 v[206:209], v167 offset:7168
	global_load_lds_dwordx4 v170, s[0:1]
	s_add_i32 m0, s23, 0xe000
	s_nop 0
	global_load_lds_dwordx4 v168, s[0:1]
	s_waitcnt vmcnt(8)
	s_waitcnt lgkmcnt(0)
	s_barrier
	s_setprio 1
	s_waitcnt lgkmcnt(0)
	v_mfma_f32_16x16x32_bf16 v[124:127], v[128:131], v[160:163], v[124:127]
	v_mfma_f32_16x16x32_bf16 v[120:123], v[136:139], v[160:163], v[120:123]
	v_mfma_f32_16x16x32_bf16 v[108:111], v[128:131], v[186:189], v[108:111]
	v_mfma_f32_16x16x32_bf16 v[104:107], v[136:139], v[186:189], v[104:107]
	v_mfma_f32_16x16x32_bf16 v[96:99], v[128:131], v[194:197], v[96:99]
	v_mfma_f32_16x16x32_bf16 v[88:91], v[136:139], v[194:197], v[88:91]
	v_mfma_f32_16x16x32_bf16 v[80:83], v[128:131], v[202:205], v[80:83]
	v_mfma_f32_16x16x32_bf16 v[72:75], v[136:139], v[202:205], v[72:75]
	v_mfma_f32_16x16x32_bf16 v[124:127], v[132:135], v[182:185], v[124:127]
	v_mfma_f32_16x16x32_bf16 v[120:123], v[140:143], v[182:185], v[120:123]
	v_mfma_f32_16x16x32_bf16 v[108:111], v[132:135], v[190:193], v[108:111]
	v_mfma_f32_16x16x32_bf16 v[104:107], v[140:143], v[190:193], v[104:107]
	v_mfma_f32_16x16x32_bf16 v[96:99], v[132:135], v[198:201], v[96:99]
	v_mfma_f32_16x16x32_bf16 v[88:91], v[140:143], v[198:201], v[88:91]
	v_mfma_f32_16x16x32_bf16 v[80:83], v[132:135], v[206:209], v[80:83]
	v_mfma_f32_16x16x32_bf16 v[72:75], v[140:143], v[206:209], v[72:75]
	s_setprio 0
	s_setprio 1
	v_mfma_f32_16x16x32_bf16 v[116:119], v[144:147], v[160:163], v[116:119]
	v_mfma_f32_16x16x32_bf16 v[112:115], v[152:155], v[160:163], v[112:115]
	v_mfma_f32_16x16x32_bf16 v[100:103], v[144:147], v[186:189], v[100:103]
	v_mfma_f32_16x16x32_bf16 v[92:95], v[152:155], v[186:189], v[92:95]
	v_mfma_f32_16x16x32_bf16 v[84:87], v[144:147], v[194:197], v[84:87]
	v_mfma_f32_16x16x32_bf16 v[76:79], v[152:155], v[194:197], v[76:79]
	v_mfma_f32_16x16x32_bf16 v[68:71], v[144:147], v[202:205], v[68:71]
	v_mfma_f32_16x16x32_bf16 v[64:67], v[152:155], v[202:205], v[64:67]
	v_mfma_f32_16x16x32_bf16 v[116:119], v[148:151], v[182:185], v[116:119]
	v_mfma_f32_16x16x32_bf16 v[112:115], v[156:159], v[182:185], v[112:115]
	v_mfma_f32_16x16x32_bf16 v[100:103], v[148:151], v[190:193], v[100:103]
	v_mfma_f32_16x16x32_bf16 v[92:95], v[156:159], v[190:193], v[92:95]
	v_mfma_f32_16x16x32_bf16 v[84:87], v[148:151], v[198:201], v[84:87]
	v_mfma_f32_16x16x32_bf16 v[76:79], v[156:159], v[198:201], v[76:79]
	v_mfma_f32_16x16x32_bf16 v[68:71], v[148:151], v[206:209], v[68:71]
	v_mfma_f32_16x16x32_bf16 v[64:67], v[156:159], v[206:209], v[64:67]
	s_setprio 0
	s_barrier
	s_add_i32 s42, s42, s20
	s_add_u32 s94, s16, s2
	s_addc_u32 s95, s17, s3
	s_add_u32 s96, s18, s2
	s_addc_u32 s97, s19, s3
	s_mov_b32 m0, s42
	ds_read_b128 v[160:163], v167 offset:16384
	ds_read_b128 v[182:185], v167 offset:17408
	ds_read_b128 v[186:189], v167 offset:18432
	ds_read_b128 v[190:193], v167 offset:19456
	ds_read_b128 v[194:197], v167 offset:20480
	ds_read_b128 v[198:201], v167 offset:21504
	ds_read_b128 v[202:205], v167 offset:22528
	ds_read_b128 v[206:209], v167 offset:23552
	global_load_lds_dwordx4 v170, s[16:17]
	s_add_i32 m0, s42, 0x2000
	s_add_u32 s42, s16, 0xb0000
	s_addc_u32 s43, s17, 0
	s_add_i32 s44, s44, s20
	global_load_lds_dwordx4 v168, s[16:17]
	s_mov_b32 m0, s44
	s_nop 0
	global_load_lds_dwordx4 v170, s[42:43]
	s_add_i32 m0, s44, 0x2000
	s_nop 0
	global_load_lds_dwordx4 v168, s[42:43]
	s_mov_b32 m0, s23
	s_nop 0
	global_load_lds_dwordx4 v170, s[18:19]
	s_mov_b32 m0, s24
	s_nop 0
	global_load_lds_dwordx4 v168, s[18:19]
	s_waitcnt vmcnt(8)
	s_waitcnt lgkmcnt(0)
	s_barrier
; #define PG8_STAGE(bufoff, gbase, voff) do { _Pragma("unroll") for (int _i = 0; _i < 2; ++_i) \
;         __builtin_amdgcn_global_load_lds((const unsigned*)((const char*)(gbase) + (voff)[_i]), (LAS unsigned*)(lds + (bufoff) + ldsw + _i * 8192), 16, 0, 0); } while (0)
; #define PG8_LDA(dst, b, h) do { _Pragma("unroll") for (int m = 0; m < 4; ++m) _Pragma("unroll") for (int k = 0; k < 2; ++k) dst[m][k] = *(const LAS bf16x8*)(lds + PG8_SA(b, h) + aoff + m * 2048 + k * 1024); } while (0)
; #define PG8_LDB(dst, b, h) do { _Pragma("unroll") for (int n = 0; n < 2; ++n) _Pragma("unroll") for (int k = 0; k < 2; ++k) dst[n][k] = *(const LAS bf16x8*)(lds + PG8_SB(b, h) + boff + n * 2048 + k * 1024); } while (0)
; #define PG8_MMA(ai, bj, At, Bt) do { __builtin_amdgcn_s_setprio(1); _Pragma("unroll") for (int m = 0; m < 4; ++m) _Pragma("unroll") for (int n = 0; n < 2; ++n) _Pragma("unroll") for (int k = 0; k < 2; ++k) \
;         acc[ai][bj][m][n] = __builtin_amdgcn_mfma_f32_16x16x32_bf16(Bt[n][k], At[m][k], acc[ai][bj][m][n], 0, 0, 0); __builtin_amdgcn_s_setprio(0); } while (0)
; #define PG8_WAIT_V(n) asm volatile("s_waitcnt vmcnt(" #n ")" ::: "memory")
; #define PG8_WAIT_L(n) asm volatile("s_waitcnt lgkmcnt(" #n ")" ::: "memory")
; #define PG8_BAR __builtin_amdgcn_s_barrier()
; #define PG8_SCHED __builtin_amdgcn_sched_barrier(0)
; template <class Epi, class Sched, bool ALIGN_EPI>
; DI void gemm_phase(LAS unsigned char* lds, const Gemm g, const Sched& S, const Epi& E) {
;     ...
;             PG8_WAIT_V(8); PG8_WAIT_L(0); PG8_BAR; PG8_MMA(0, 0, At, B0); PG8_MMA(0, 1, At, B1); PG8_BAR; PG8_SCHED;
;             PG8_LDA(At, 0, 1); PG8_STAGE(PG8_SB(0, 0), b2, voffA); PG8_STAGE(PG8_SB(0, 1), b2 + hstep, voffA); PG8_STAGE(PG8_SA(0, 0), a2, voffA);
;             PG8_WAIT_V(8); PG8_WAIT_L(0); PG8_BAR; PG8_MMA(1, 0, At, B0); PG8_MMA(1, 1, At, B1); PG8_BAR; PG8_SCHED;
;             PG8_LDB(B0, 1, 0); PG8_LDB(B1, 1, 1); PG8_SCHED; PG8_LDA(At, 1, 0); PG8_STAGE(PG8_SA(0, 1), a2 + hstep, voffA);
;             PG8_WAIT_V(8); PG8_WAIT_L(0); PG8_BAR; PG8_MMA(0, 0, At, B0); PG8_MMA(0, 1, At, B1); PG8_BAR; PG8_SCHED;
;             PG8_LDA(At, 1, 1); PG8_STAGE(PG8_SB(1, 0), b3, voffA); PG8_STAGE(PG8_SB(1, 1), b3 + hstep, voffA); PG8_STAGE(PG8_SA(1, 0), a3, voffA);
;             PG8_WAIT_V(8); PG8_WAIT_L(0); PG8_BAR; PG8_MMA(1, 0, At, B0); PG8_MMA(1, 1, At, B1); PG8_BAR; PG8_SCHED;
	s_setprio 1
	s_waitcnt lgkmcnt(0)
	v_mfma_f32_16x16x32_bf16 v[60:63], v[128:131], v[160:163], v[60:63]
	v_mfma_f32_16x16x32_bf16 v[56:59], v[136:139], v[160:163], v[56:59]
	v_mfma_f32_16x16x32_bf16 v[48:51], v[128:131], v[186:189], v[48:51]
	v_mfma_f32_16x16x32_bf16 v[40:43], v[136:139], v[186:189], v[40:43]
	v_mfma_f32_16x16x32_bf16 v[32:35], v[128:131], v[194:197], v[32:35]
	v_mfma_f32_16x16x32_bf16 v[24:27], v[136:139], v[194:197], v[24:27]
	v_mfma_f32_16x16x32_bf16 v[16:19], v[128:131], v[202:205], v[16:19]
	v_mfma_f32_16x16x32_bf16 v[8:11], v[136:139], v[202:205], v[8:11]
	v_mfma_f32_16x16x32_bf16 v[60:63], v[132:135], v[182:185], v[60:63]
	v_mfma_f32_16x16x32_bf16 v[56:59], v[140:143], v[182:185], v[56:59]
	v_mfma_f32_16x16x32_bf16 v[48:51], v[132:135], v[190:193], v[48:51]
	v_mfma_f32_16x16x32_bf16 v[40:43], v[140:143], v[190:193], v[40:43]
	v_mfma_f32_16x16x32_bf16 v[32:35], v[132:135], v[198:201], v[32:35]
	v_mfma_f32_16x16x32_bf16 v[24:27], v[140:143], v[198:201], v[24:27]
	v_mfma_f32_16x16x32_bf16 v[16:19], v[132:135], v[206:209], v[16:19]
	v_mfma_f32_16x16x32_bf16 v[8:11], v[140:143], v[206:209], v[8:11]
	s_setprio 0
	s_setprio 1
	v_mfma_f32_16x16x32_bf16 v[52:55], v[144:147], v[160:163], v[52:55]
	v_mfma_f32_16x16x32_bf16 v[44:47], v[152:155], v[160:163], v[44:47]
	v_mfma_f32_16x16x32_bf16 v[36:39], v[144:147], v[186:189], v[36:39]
	v_mfma_f32_16x16x32_bf16 v[28:31], v[152:155], v[186:189], v[28:31]
	v_mfma_f32_16x16x32_bf16 v[20:23], v[144:147], v[194:197], v[20:23]
	v_mfma_f32_16x16x32_bf16 v[12:15], v[152:155], v[194:197], v[12:15]
	v_mfma_f32_16x16x32_bf16 v[4:7], v[144:147], v[202:205], v[4:7]
	v_mfma_f32_16x16x32_bf16 v[0:3], v[152:155], v[202:205], v[0:3]
	v_mfma_f32_16x16x32_bf16 v[52:55], v[148:151], v[182:185], v[52:55]
	v_mfma_f32_16x16x32_bf16 v[44:47], v[156:159], v[182:185], v[44:47]
	v_mfma_f32_16x16x32_bf16 v[36:39], v[148:151], v[190:193], v[36:39]
	v_mfma_f32_16x16x32_bf16 v[28:31], v[156:159], v[190:193], v[28:31]
	v_mfma_f32_16x16x32_bf16 v[20:23], v[148:151], v[198:201], v[20:23]
	v_mfma_f32_16x16x32_bf16 v[12:15], v[156:159], v[198:201], v[12:15]
	v_mfma_f32_16x16x32_bf16 v[4:7], v[148:151], v[206:209], v[4:7]
	v_mfma_f32_16x16x32_bf16 v[0:3], v[156:159], v[206:209], v[0:3]
	s_setprio 0
	s_barrier
	s_add_i32 s42, 0, 0x18000
	s_add_i32 s43, 0, 0x1c000
	v_add_u32_e32 v140, s42, v165
	v_add_u32_e32 v156, s43, v165
	ds_read_b128 v[128:131], v140
	ds_read_b128 v[132:135], v140 offset:1024
	ds_read_b128 v[136:139], v140 offset:2048
	ds_read_b128 v[140:143], v140 offset:3072
	ds_read_b128 v[144:147], v156
	ds_read_b128 v[148:151], v156 offset:1024
	ds_read_b128 v[152:155], v156 offset:2048
	ds_read_b128 v[156:159], v156 offset:3072
	s_add_u32 s18, s18, 0xb0000
	s_addc_u32 s19, s19, 0
	s_mov_b32 m0, s25
	ds_read_b128 v[160:163], v167 offset:32768
	ds_read_b128 v[182:185], v167 offset:33792
	ds_read_b128 v[186:189], v167 offset:34816
	ds_read_b128 v[190:193], v167 offset:35840
	ds_read_b128 v[194:197], v167 offset:36864
	ds_read_b128 v[198:201], v167 offset:37888
	ds_read_b128 v[202:205], v167 offset:38912
	ds_read_b128 v[206:209], v167 offset:39936
	global_load_lds_dwordx4 v170, s[18:19]
	s_mov_b32 m0, s26
	s_nop 0
	global_load_lds_dwordx4 v168, s[18:19]
	s_waitcnt vmcnt(8)
	s_waitcnt lgkmcnt(0)
	s_barrier
	s_setprio 1
	s_waitcnt lgkmcnt(0)
	v_mfma_f32_16x16x32_bf16 v[124:127], v[128:131], v[160:163], v[124:127]
	v_mfma_f32_16x16x32_bf16 v[120:123], v[136:139], v[160:163], v[120:123]
	v_mfma_f32_16x16x32_bf16 v[108:111], v[128:131], v[186:189], v[108:111]
	v_mfma_f32_16x16x32_bf16 v[104:107], v[136:139], v[186:189], v[104:107]
	v_mfma_f32_16x16x32_bf16 v[96:99], v[128:131], v[194:197], v[96:99]
	v_mfma_f32_16x16x32_bf16 v[88:91], v[136:139], v[194:197], v[88:91]
	v_mfma_f32_16x16x32_bf16 v[80:83], v[128:131], v[202:205], v[80:83]
	v_mfma_f32_16x16x32_bf16 v[72:75], v[136:139], v[202:205], v[72:75]
	v_mfma_f32_16x16x32_bf16 v[124:127], v[132:135], v[182:185], v[124:127]
	v_mfma_f32_16x16x32_bf16 v[120:123], v[140:143], v[182:185], v[120:123]
	v_mfma_f32_16x16x32_bf16 v[108:111], v[132:135], v[190:193], v[108:111]
	v_mfma_f32_16x16x32_bf16 v[104:107], v[140:143], v[190:193], v[104:107]
	v_mfma_f32_16x16x32_bf16 v[96:99], v[132:135], v[198:201], v[96:99]
	v_mfma_f32_16x16x32_bf16 v[88:91], v[140:143], v[198:201], v[88:91]
	v_mfma_f32_16x16x32_bf16 v[80:83], v[132:135], v[206:209], v[80:83]
	v_mfma_f32_16x16x32_bf16 v[72:75], v[140:143], v[206:209], v[72:75]
	s_setprio 0
	s_setprio 1
	v_mfma_f32_16x16x32_bf16 v[116:119], v[144:147], v[160:163], v[116:119]
	v_mfma_f32_16x16x32_bf16 v[112:115], v[152:155], v[160:163], v[112:115]
	v_mfma_f32_16x16x32_bf16 v[100:103], v[144:147], v[186:189], v[100:103]
	v_mfma_f32_16x16x32_bf16 v[92:95], v[152:155], v[186:189], v[92:95]
	v_mfma_f32_16x16x32_bf16 v[84:87], v[144:147], v[194:197], v[84:87]
	v_mfma_f32_16x16x32_bf16 v[76:79], v[152:155], v[194:197], v[76:79]
	v_mfma_f32_16x16x32_bf16 v[68:71], v[144:147], v[202:205], v[68:71]
	v_mfma_f32_16x16x32_bf16 v[64:67], v[152:155], v[202:205], v[64:67]
	v_mfma_f32_16x16x32_bf16 v[116:119], v[148:151], v[182:185], v[116:119]
	v_mfma_f32_16x16x32_bf16 v[112:115], v[156:159], v[182:185], v[112:115]
	v_mfma_f32_16x16x32_bf16 v[100:103], v[148:151], v[190:193], v[100:103]
	v_mfma_f32_16x16x32_bf16 v[92:95], v[156:159], v[190:193], v[92:95]
	v_mfma_f32_16x16x32_bf16 v[84:87], v[148:151], v[198:201], v[84:87]
	v_mfma_f32_16x16x32_bf16 v[76:79], v[156:159], v[198:201], v[76:79]
	v_mfma_f32_16x16x32_bf16 v[68:71], v[148:151], v[206:209], v[68:71]
	v_mfma_f32_16x16x32_bf16 v[64:67], v[156:159], v[206:209], v[64:67]
	s_setprio 0
	s_barrier
; #define PG8_STAGE(bufoff, gbase, voff) do { _Pragma("unroll") for (int _i = 0; _i < 2; ++_i) \
;         __builtin_amdgcn_global_load_lds((const unsigned*)((const char*)(gbase) + (voff)[_i]), (LAS unsigned*)(lds + (bufoff) + ldsw + _i * 8192), 16, 0, 0); } while (0)
; #define PG8_LDA(dst, b, h) do { _Pragma("unroll") for (int m = 0; m < 4; ++m) _Pragma("unroll") for (int k = 0; k < 2; ++k) dst[m][k] = *(const LAS bf16x8*)(lds + PG8_SA(b, h) + aoff + m * 2048 + k * 1024); } while (0)
; #define PG8_MMA(ai, bj, At, Bt) do { __builtin_amdgcn_s_setprio(1); _Pragma("unroll") for (int m = 0; m < 4; ++m) _Pragma("unroll") for (int n = 0; n < 2; ++n) _Pragma("unroll") for (int k = 0; k < 2; ++k) \
;         acc[ai][bj][m][n] = __builtin_amdgcn_mfma_f32_16x16x32_bf16(Bt[n][k], At[m][k], acc[ai][bj][m][n], 0, 0, 0); __builtin_amdgcn_s_setprio(0); } while (0)
; #define PG8_WAIT_V(n) asm volatile("s_waitcnt vmcnt(" #n ")" ::: "memory")
; #define PG8_WAIT_L(n) asm volatile("s_waitcnt lgkmcnt(" #n ")" ::: "memory")
; #define PG8_BAR __builtin_amdgcn_s_barrier()
; #define PG8_SCHED __builtin_amdgcn_sched_barrier(0)
; template <class Epi, class Sched, bool ALIGN_EPI>
; DI void gemm_phase(LAS unsigned char* lds, const Gemm g, const Sched& S, const Epi& E) {
;     ...
;             PG8_LDA(At, 1, 1); PG8_STAGE(PG8_SB(1, 0), b3, voffA); PG8_STAGE(PG8_SB(1, 1), b3 + hstep, voffA); PG8_STAGE(PG8_SA(1, 0), a3, voffA);
;             PG8_WAIT_V(8); PG8_WAIT_L(0); PG8_BAR; PG8_MMA(1, 0, At, B0); PG8_MMA(1, 1, At, B1); PG8_BAR; PG8_SCHED;
;         }
	s_add_i32 s18, s42, s20
	s_mov_b32 m0, s18
	ds_read_b128 v[160:163], v167 offset:49152
	ds_read_b128 v[182:185], v167 offset:50176
	ds_read_b128 v[186:189], v167 offset:51200
	ds_read_b128 v[190:193], v167 offset:52224
	ds_read_b128 v[194:197], v167 offset:53248
	ds_read_b128 v[198:201], v167 offset:54272
	ds_read_b128 v[202:205], v167 offset:55296
	ds_read_b128 v[206:209], v167 offset:56320
	global_load_lds_dwordx4 v170, s[94:95]
	s_add_i32 m0, s18, 0x2000
	s_add_u32 s16, s16, 0xb0080
	s_addc_u32 s17, s17, 0
	s_add_i32 s18, s43, s20
	global_load_lds_dwordx4 v168, s[94:95]
	s_mov_b32 m0, s18
	s_nop 0
	global_load_lds_dwordx4 v170, s[16:17]
	s_add_i32 m0, s18, 0x2000
	s_nop 0
	global_load_lds_dwordx4 v168, s[16:17]
	s_mov_b32 m0, s27
	s_nop 0
	global_load_lds_dwordx4 v170, s[96:97]
	s_mov_b32 m0, s28
	s_nop 0
	global_load_lds_dwordx4 v168, s[96:97]
	s_waitcnt vmcnt(8)
	s_waitcnt lgkmcnt(0)
	s_barrier
	s_setprio 1
	s_waitcnt lgkmcnt(0)
	v_mfma_f32_16x16x32_bf16 v[60:63], v[128:131], v[160:163], v[60:63]
	v_mfma_f32_16x16x32_bf16 v[56:59], v[136:139], v[160:163], v[56:59]
	v_mfma_f32_16x16x32_bf16 v[48:51], v[128:131], v[186:189], v[48:51]
	v_mfma_f32_16x16x32_bf16 v[40:43], v[136:139], v[186:189], v[40:43]
	v_mfma_f32_16x16x32_bf16 v[32:35], v[128:131], v[194:197], v[32:35]
	v_mfma_f32_16x16x32_bf16 v[24:27], v[136:139], v[194:197], v[24:27]
	v_mfma_f32_16x16x32_bf16 v[16:19], v[128:131], v[202:205], v[16:19]
	v_mfma_f32_16x16x32_bf16 v[8:11], v[136:139], v[202:205], v[8:11]
	v_mfma_f32_16x16x32_bf16 v[60:63], v[132:135], v[182:185], v[60:63]
	v_mfma_f32_16x16x32_bf16 v[56:59], v[140:143], v[182:185], v[56:59]
	v_mfma_f32_16x16x32_bf16 v[48:51], v[132:135], v[190:193], v[48:51]
	v_mfma_f32_16x16x32_bf16 v[40:43], v[140:143], v[190:193], v[40:43]
	v_mfma_f32_16x16x32_bf16 v[32:35], v[132:135], v[198:201], v[32:35]
	v_mfma_f32_16x16x32_bf16 v[24:27], v[140:143], v[198:201], v[24:27]
	v_mfma_f32_16x16x32_bf16 v[16:19], v[132:135], v[206:209], v[16:19]
	v_mfma_f32_16x16x32_bf16 v[8:11], v[140:143], v[206:209], v[8:11]
	s_setprio 0
	s_setprio 1
	v_mfma_f32_16x16x32_bf16 v[52:55], v[144:147], v[160:163], v[52:55]
	v_mfma_f32_16x16x32_bf16 v[44:47], v[152:155], v[160:163], v[44:47]
	v_mfma_f32_16x16x32_bf16 v[36:39], v[144:147], v[186:189], v[36:39]
	v_mfma_f32_16x16x32_bf16 v[28:31], v[152:155], v[186:189], v[28:31]
	v_mfma_f32_16x16x32_bf16 v[20:23], v[144:147], v[194:197], v[20:23]
	v_mfma_f32_16x16x32_bf16 v[12:15], v[152:155], v[194:197], v[12:15]
	v_mfma_f32_16x16x32_bf16 v[4:7], v[144:147], v[202:205], v[4:7]
	v_mfma_f32_16x16x32_bf16 v[0:3], v[152:155], v[202:205], v[0:3]
	v_mfma_f32_16x16x32_bf16 v[52:55], v[148:151], v[182:185], v[52:55]
	v_mfma_f32_16x16x32_bf16 v[44:47], v[156:159], v[182:185], v[44:47]
	v_mfma_f32_16x16x32_bf16 v[36:39], v[148:151], v[190:193], v[36:39]
	v_mfma_f32_16x16x32_bf16 v[28:31], v[156:159], v[190:193], v[28:31]
	v_mfma_f32_16x16x32_bf16 v[20:23], v[148:151], v[198:201], v[20:23]
	v_mfma_f32_16x16x32_bf16 v[12:15], v[156:159], v[198:201], v[12:15]
	v_mfma_f32_16x16x32_bf16 v[4:7], v[148:151], v[206:209], v[4:7]
	v_mfma_f32_16x16x32_bf16 v[0:3], v[156:159], v[206:209], v[0:3]
	s_setprio 0
	s_barrier
	s_add_i32 s37, s37, 2
	s_add_u32 s0, s0, 0x100
	s_addc_u32 s1, s1, 0
	s_add_u32 s35, s35, 0x100
	s_addc_u32 s36, s36, 0
	s_cmp_gt_u32 s37, 41
	s_cbranch_scc0 .LBB0_791
	s_and_b64 vcc, exec, s[10:11]
	s_cbranch_vccz .LBB0_794
	s_barrier

; #define PG8_STAGE(bufoff, gbase, voff) do { _Pragma("unroll") for (int _i = 0; _i < 2; ++_i) \
;         __builtin_amdgcn_global_load_lds((const unsigned*)((const char*)(gbase) + (voff)[_i]), (LAS unsigned*)(lds + (bufoff) + ldsw + _i * 8192), 16, 0, 0); } while (0)
; #define PG8_LDA(dst, b, h) do { _Pragma("unroll") for (int m = 0; m < 4; ++m) _Pragma("unroll") for (int k = 0; k < 2; ++k) dst[m][k] = *(const LAS bf16x8*)(lds + PG8_SA(b, h) + aoff + m * 2048 + k * 1024); } while (0)
; #define PG8_LDB(dst, b, h) do { _Pragma("unroll") for (int n = 0; n < 2; ++n) _Pragma("unroll") for (int k = 0; k < 2; ++k) dst[n][k] = *(const LAS bf16x8*)(lds + PG8_SB(b, h) + boff + n * 2048 + k * 1024); } while (0)
; #define PG8_MMA(ai, bj, At, Bt) do { __builtin_amdgcn_s_setprio(1); _Pragma("unroll") for (int m = 0; m < 4; ++m) _Pragma("unroll") for (int n = 0; n < 2; ++n) _Pragma("unroll") for (int k = 0; k < 2; ++k) \
;         acc[ai][bj][m][n] = __builtin_amdgcn_mfma_f32_16x16x32_bf16(Bt[n][k], At[m][k], acc[ai][bj][m][n], 0, 0, 0); __builtin_amdgcn_s_setprio(0); } while (0)
; #define PG8_WAIT_V(n) asm volatile("s_waitcnt vmcnt(" #n ")" ::: "memory")
; #define PG8_WAIT_L(n) asm volatile("s_waitcnt lgkmcnt(" #n ")" ::: "memory")
; #define PG8_BAR __builtin_amdgcn_s_barrier()
; #define PG8_SCHED __builtin_amdgcn_sched_barrier(0)
; template <class Epi, class Sched, bool ALIGN_EPI>
; DI void gemm_phase(LAS unsigned char* lds, const Gemm g, const Sched& S, const Epi& E) {
;     ...
;             const bool last = (t == nt - 2);
;             const char* a1 = cA + (size_t)(t + 1) * kstep;
;             const char* a2 = last ? nA : cA + (size_t)(t + 2) * kstep; const char* b2 = last ? nB : cB + (size_t)(t + 2) * kstep;
;             const char* a3 = a2 + kstep; const char* b3 = b2 + kstep;
;             PG8_LDB(B0, 0, 0); PG8_LDB(B1, 0, 1); PG8_SCHED; PG8_LDA(At, 0, 0); PG8_STAGE(PG8_SA(1, 1), a1 + hstep, voffA);
;             PG8_WAIT_V(8); PG8_WAIT_L(0); PG8_BAR; PG8_MMA(0, 0, At, B0); PG8_MMA(0, 1, At, B1); PG8_BAR; PG8_SCHED;
;             PG8_LDA(At, 0, 1); PG8_STAGE(PG8_SB(0, 0), b2, voffA); PG8_STAGE(PG8_SB(0, 1), b2 + hstep, voffA); PG8_STAGE(PG8_SA(0, 0), a2, voffA);
;             PG8_WAIT_V(8); PG8_WAIT_L(0); PG8_BAR; PG8_MMA(1, 0, At, B0); PG8_MMA(1, 1, At, B1); PG8_BAR; PG8_SCHED;
.LBB0_957:
	s_add_u32 s16, s0, 0xfffc0080
	s_addc_u32 s17, s1, -1
	s_add_i32 s43, 0, 0x10000
	s_cmp_eq_u32 s42, 12
	s_cselect_b32 s19, s5, s17
	s_cselect_b32 s18, s34, s16
	s_cselect_b32 s17, s15, s37
	s_cselect_b32 s16, s35, s36
	s_add_i32 s50, 0, 0x14000
	v_add_u32_e32 v144, s43, v133
	v_add_u32_e32 v160, s50, v133
	ds_read_b128 v[128:131], v144
	ds_read_b128 v[136:139], v144 offset:1024
	ds_read_b128 v[140:143], v144 offset:2048
	ds_read_b128 v[144:147], v144 offset:3072
	ds_read_b128 v[148:151], v160
	ds_read_b128 v[152:155], v160 offset:1024
	ds_read_b128 v[156:159], v160 offset:2048
	ds_read_b128 v[160:163], v160 offset:3072
	s_add_i32 m0, s22, 0xc000
	ds_read_b128 v[164:167], v135
	ds_read_b128 v[182:185], v135 offset:1024
	ds_read_b128 v[186:189], v135 offset:2048
	ds_read_b128 v[190:193], v135 offset:3072
	ds_read_b128 v[194:197], v135 offset:4096
	ds_read_b128 v[198:201], v135 offset:5120
	ds_read_b128 v[202:205], v135 offset:6144
	ds_read_b128 v[206:209], v135 offset:7168
	global_load_lds_dwordx4 v178, s[0:1]
	s_add_i32 m0, s22, 0xe000
	s_nop 0
	global_load_lds_dwordx4 v180, s[0:1]
	s_waitcnt vmcnt(8)
	s_waitcnt lgkmcnt(0)
	s_barrier
	s_setprio 1
	s_waitcnt lgkmcnt(0)
	v_mfma_f32_16x16x32_bf16 v[124:127], v[128:131], v[164:167], v[124:127]
	v_mfma_f32_16x16x32_bf16 v[120:123], v[140:143], v[164:167], v[120:123]
	v_mfma_f32_16x16x32_bf16 v[108:111], v[128:131], v[186:189], v[108:111]
	v_mfma_f32_16x16x32_bf16 v[104:107], v[140:143], v[186:189], v[104:107]
	v_mfma_f32_16x16x32_bf16 v[92:95], v[128:131], v[194:197], v[92:95]
	v_mfma_f32_16x16x32_bf16 v[88:91], v[140:143], v[194:197], v[88:91]
	v_mfma_f32_16x16x32_bf16 v[76:79], v[128:131], v[202:205], v[76:79]
	v_mfma_f32_16x16x32_bf16 v[72:75], v[140:143], v[202:205], v[72:75]
	v_mfma_f32_16x16x32_bf16 v[124:127], v[136:139], v[182:185], v[124:127]
	v_mfma_f32_16x16x32_bf16 v[120:123], v[144:147], v[182:185], v[120:123]
	v_mfma_f32_16x16x32_bf16 v[108:111], v[136:139], v[190:193], v[108:111]
	v_mfma_f32_16x16x32_bf16 v[104:107], v[144:147], v[190:193], v[104:107]
	v_mfma_f32_16x16x32_bf16 v[92:95], v[136:139], v[198:201], v[92:95]
	v_mfma_f32_16x16x32_bf16 v[88:91], v[144:147], v[198:201], v[88:91]
	v_mfma_f32_16x16x32_bf16 v[76:79], v[136:139], v[206:209], v[76:79]
	v_mfma_f32_16x16x32_bf16 v[72:75], v[144:147], v[206:209], v[72:75]
	s_setprio 0
	s_setprio 1
	v_mfma_f32_16x16x32_bf16 v[116:119], v[148:151], v[164:167], v[116:119]
	v_mfma_f32_16x16x32_bf16 v[112:115], v[156:159], v[164:167], v[112:115]
	v_mfma_f32_16x16x32_bf16 v[100:103], v[148:151], v[186:189], v[100:103]
	v_mfma_f32_16x16x32_bf16 v[96:99], v[156:159], v[186:189], v[96:99]
	v_mfma_f32_16x16x32_bf16 v[84:87], v[148:151], v[194:197], v[84:87]
	v_mfma_f32_16x16x32_bf16 v[80:83], v[156:159], v[194:197], v[80:83]
	v_mfma_f32_16x16x32_bf16 v[68:71], v[148:151], v[202:205], v[68:71]
	v_mfma_f32_16x16x32_bf16 v[64:67], v[156:159], v[202:205], v[64:67]
	v_mfma_f32_16x16x32_bf16 v[116:119], v[152:155], v[182:185], v[116:119]
	v_mfma_f32_16x16x32_bf16 v[112:115], v[160:163], v[182:185], v[112:115]
	v_mfma_f32_16x16x32_bf16 v[100:103], v[152:155], v[190:193], v[100:103]
	v_mfma_f32_16x16x32_bf16 v[96:99], v[160:163], v[190:193], v[96:99]
	v_mfma_f32_16x16x32_bf16 v[84:87], v[152:155], v[198:201], v[84:87]
	v_mfma_f32_16x16x32_bf16 v[80:83], v[160:163], v[198:201], v[80:83]
	v_mfma_f32_16x16x32_bf16 v[68:71], v[152:155], v[206:209], v[68:71]
	v_mfma_f32_16x16x32_bf16 v[64:67], v[160:163], v[206:209], v[64:67]
	s_setprio 0
	s_barrier
	s_add_i32 s43, s43, s20
	s_add_u32 s94, s16, s2
	s_addc_u32 s95, s17, s3
	s_add_u32 s96, s18, s2
	s_addc_u32 s97, s19, s3
	s_mov_b32 m0, s43
	ds_read_b128 v[164:167], v135 offset:16384
	ds_read_b128 v[182:185], v135 offset:17408
	ds_read_b128 v[186:189], v135 offset:18432
	ds_read_b128 v[190:193], v135 offset:19456
	ds_read_b128 v[194:197], v135 offset:20480
	ds_read_b128 v[198:201], v135 offset:21504
	ds_read_b128 v[202:205], v135 offset:22528
	ds_read_b128 v[206:209], v135 offset:23552
	global_load_lds_dwordx4 v174, s[16:17]
	s_add_i32 m0, s43, 0x2000
	s_add_u32 s48, s16, 0x40000
	s_addc_u32 s49, s17, 0
	s_add_i32 s43, s50, s20
	global_load_lds_dwordx4 v176, s[16:17]
	s_mov_b32 m0, s43
	s_nop 0
	global_load_lds_dwordx4 v174, s[48:49]
	s_add_i32 m0, s43, 0x2000
	s_nop 0
	global_load_lds_dwordx4 v176, s[48:49]
	s_mov_b32 m0, s22
	s_nop 0
	global_load_lds_dwordx4 v174, s[18:19]
	s_mov_b32 m0, s23
	s_nop 0
	global_load_lds_dwordx4 v176, s[18:19]
	s_waitcnt vmcnt(8)
	s_waitcnt lgkmcnt(0)
	s_barrier
; #define PG8_STAGE(bufoff, gbase, voff) do { _Pragma("unroll") for (int _i = 0; _i < 2; ++_i) \
;         __builtin_amdgcn_global_load_lds((const unsigned*)((const char*)(gbase) + (voff)[_i]), (LAS unsigned*)(lds + (bufoff) + ldsw + _i * 8192), 16, 0, 0); } while (0)
; #define PG8_LDA(dst, b, h) do { _Pragma("unroll") for (int m = 0; m < 4; ++m) _Pragma("unroll") for (int k = 0; k < 2; ++k) dst[m][k] = *(const LAS bf16x8*)(lds + PG8_SA(b, h) + aoff + m * 2048 + k * 1024); } while (0)
; #define PG8_LDB(dst, b, h) do { _Pragma("unroll") for (int n = 0; n < 2; ++n) _Pragma("unroll") for (int k = 0; k < 2; ++k) dst[n][k] = *(const LAS bf16x8*)(lds + PG8_SB(b, h) + boff + n * 2048 + k * 1024); } while (0)
; #define PG8_MMA(ai, bj, At, Bt) do { __builtin_amdgcn_s_setprio(1); _Pragma("unroll") for (int m = 0; m < 4; ++m) _Pragma("unroll") for (int n = 0; n < 2; ++n) _Pragma("unroll") for (int k = 0; k < 2; ++k) \
;         acc[ai][bj][m][n] = __builtin_amdgcn_mfma_f32_16x16x32_bf16(Bt[n][k], At[m][k], acc[ai][bj][m][n], 0, 0, 0); __builtin_amdgcn_s_setprio(0); } while (0)
; #define PG8_WAIT_V(n) asm volatile("s_waitcnt vmcnt(" #n ")" ::: "memory")
; #define PG8_WAIT_L(n) asm volatile("s_waitcnt lgkmcnt(" #n ")" ::: "memory")
; #define PG8_BAR __builtin_amdgcn_s_barrier()
; #define PG8_SCHED __builtin_amdgcn_sched_barrier(0)
; template <class Epi, class Sched, bool ALIGN_EPI>
; DI void gemm_phase(LAS unsigned char* lds, const Gemm g, const Sched& S, const Epi& E) {
;     ...
;             PG8_WAIT_V(8); PG8_WAIT_L(0); PG8_BAR; PG8_MMA(1, 0, At, B0); PG8_MMA(1, 1, At, B1); PG8_BAR; PG8_SCHED;
;             PG8_LDB(B0, 1, 0); PG8_LDB(B1, 1, 1); PG8_SCHED; PG8_LDA(At, 1, 0); PG8_STAGE(PG8_SA(0, 1), a2 + hstep, voffA);
;             PG8_WAIT_V(8); PG8_WAIT_L(0); PG8_BAR; PG8_MMA(0, 0, At, B0); PG8_MMA(0, 1, At, B1); PG8_BAR; PG8_SCHED;
	s_setprio 1
	s_waitcnt lgkmcnt(0)
	v_mfma_f32_16x16x32_bf16 v[60:63], v[128:131], v[164:167], v[60:63]
	v_mfma_f32_16x16x32_bf16 v[56:59], v[140:143], v[164:167], v[56:59]
	v_mfma_f32_16x16x32_bf16 v[44:47], v[128:131], v[186:189], v[44:47]
	v_mfma_f32_16x16x32_bf16 v[40:43], v[140:143], v[186:189], v[40:43]
	v_mfma_f32_16x16x32_bf16 v[28:31], v[128:131], v[194:197], v[28:31]
	v_mfma_f32_16x16x32_bf16 v[24:27], v[140:143], v[194:197], v[24:27]
	v_mfma_f32_16x16x32_bf16 v[12:15], v[128:131], v[202:205], v[12:15]
	v_mfma_f32_16x16x32_bf16 v[8:11], v[140:143], v[202:205], v[8:11]
	v_mfma_f32_16x16x32_bf16 v[60:63], v[136:139], v[182:185], v[60:63]
	v_mfma_f32_16x16x32_bf16 v[56:59], v[144:147], v[182:185], v[56:59]
	v_mfma_f32_16x16x32_bf16 v[44:47], v[136:139], v[190:193], v[44:47]
	v_mfma_f32_16x16x32_bf16 v[40:43], v[144:147], v[190:193], v[40:43]
	v_mfma_f32_16x16x32_bf16 v[28:31], v[136:139], v[198:201], v[28:31]
	v_mfma_f32_16x16x32_bf16 v[24:27], v[144:147], v[198:201], v[24:27]
	v_mfma_f32_16x16x32_bf16 v[12:15], v[136:139], v[206:209], v[12:15]
	v_mfma_f32_16x16x32_bf16 v[8:11], v[144:147], v[206:209], v[8:11]
	s_setprio 0
	s_setprio 1
	v_mfma_f32_16x16x32_bf16 v[52:55], v[148:151], v[164:167], v[52:55]
	v_mfma_f32_16x16x32_bf16 v[48:51], v[156:159], v[164:167], v[48:51]
	v_mfma_f32_16x16x32_bf16 v[36:39], v[148:151], v[186:189], v[36:39]
	v_mfma_f32_16x16x32_bf16 v[32:35], v[156:159], v[186:189], v[32:35]
	v_mfma_f32_16x16x32_bf16 v[20:23], v[148:151], v[194:197], v[20:23]
	v_mfma_f32_16x16x32_bf16 v[16:19], v[156:159], v[194:197], v[16:19]
	v_mfma_f32_16x16x32_bf16 v[4:7], v[148:151], v[202:205], v[4:7]
	v_mfma_f32_16x16x32_bf16 v[0:3], v[156:159], v[202:205], v[0:3]
	v_mfma_f32_16x16x32_bf16 v[52:55], v[152:155], v[182:185], v[52:55]
	v_mfma_f32_16x16x32_bf16 v[48:51], v[160:163], v[182:185], v[48:51]
	v_mfma_f32_16x16x32_bf16 v[36:39], v[152:155], v[190:193], v[36:39]
	v_mfma_f32_16x16x32_bf16 v[32:35], v[160:163], v[190:193], v[32:35]
	v_mfma_f32_16x16x32_bf16 v[20:23], v[152:155], v[198:201], v[20:23]
	v_mfma_f32_16x16x32_bf16 v[16:19], v[160:163], v[198:201], v[16:19]
	v_mfma_f32_16x16x32_bf16 v[4:7], v[152:155], v[206:209], v[4:7]
	v_mfma_f32_16x16x32_bf16 v[0:3], v[160:163], v[206:209], v[0:3]
	s_setprio 0
	s_barrier
	s_add_i32 s43, 0, 0x18000
	s_add_i32 s48, 0, 0x1c000
	v_add_u32_e32 v144, s43, v133
	v_add_u32_e32 v160, s48, v133
	ds_read_b128 v[128:131], v144
	ds_read_b128 v[136:139], v144 offset:1024
	ds_read_b128 v[140:143], v144 offset:2048
	ds_read_b128 v[144:147], v144 offset:3072
	ds_read_b128 v[148:151], v160
	ds_read_b128 v[152:155], v160 offset:1024
	ds_read_b128 v[156:159], v160 offset:2048
	ds_read_b128 v[160:163], v160 offset:3072
	s_add_u32 s18, s18, 0x40000
	s_addc_u32 s19, s19, 0
	s_mov_b32 m0, s24
	ds_read_b128 v[164:167], v135 offset:32768
	ds_read_b128 v[182:185], v135 offset:33792
	ds_read_b128 v[186:189], v135 offset:34816
	ds_read_b128 v[190:193], v135 offset:35840
	ds_read_b128 v[194:197], v135 offset:36864
	ds_read_b128 v[198:201], v135 offset:37888
	ds_read_b128 v[202:205], v135 offset:38912
	ds_read_b128 v[206:209], v135 offset:39936
	global_load_lds_dwordx4 v174, s[18:19]
	s_mov_b32 m0, s25
	s_nop 0
	global_load_lds_dwordx4 v176, s[18:19]
	s_waitcnt vmcnt(8)
	s_waitcnt lgkmcnt(0)
	s_barrier
	s_setprio 1
	s_waitcnt lgkmcnt(0)
	v_mfma_f32_16x16x32_bf16 v[124:127], v[128:131], v[164:167], v[124:127]
	v_mfma_f32_16x16x32_bf16 v[120:123], v[140:143], v[164:167], v[120:123]
	v_mfma_f32_16x16x32_bf16 v[108:111], v[128:131], v[186:189], v[108:111]
	v_mfma_f32_16x16x32_bf16 v[104:107], v[140:143], v[186:189], v[104:107]
	v_mfma_f32_16x16x32_bf16 v[92:95], v[128:131], v[194:197], v[92:95]
	v_mfma_f32_16x16x32_bf16 v[88:91], v[140:143], v[194:197], v[88:91]
	v_mfma_f32_16x16x32_bf16 v[76:79], v[128:131], v[202:205], v[76:79]
	v_mfma_f32_16x16x32_bf16 v[72:75], v[140:143], v[202:205], v[72:75]
	v_mfma_f32_16x16x32_bf16 v[124:127], v[136:139], v[182:185], v[124:127]
	v_mfma_f32_16x16x32_bf16 v[120:123], v[144:147], v[182:185], v[120:123]
	v_mfma_f32_16x16x32_bf16 v[108:111], v[136:139], v[190:193], v[108:111]
	v_mfma_f32_16x16x32_bf16 v[104:107], v[144:147], v[190:193], v[104:107]
	v_mfma_f32_16x16x32_bf16 v[92:95], v[136:139], v[198:201], v[92:95]
	v_mfma_f32_16x16x32_bf16 v[88:91], v[144:147], v[198:201], v[88:91]
	v_mfma_f32_16x16x32_bf16 v[76:79], v[136:139], v[206:209], v[76:79]
	v_mfma_f32_16x16x32_bf16 v[72:75], v[144:147], v[206:209], v[72:75]
	s_setprio 0
	s_setprio 1
	v_mfma_f32_16x16x32_bf16 v[116:119], v[148:151], v[164:167], v[116:119]
	v_mfma_f32_16x16x32_bf16 v[112:115], v[156:159], v[164:167], v[112:115]
	v_mfma_f32_16x16x32_bf16 v[100:103], v[148:151], v[186:189], v[100:103]
	v_mfma_f32_16x16x32_bf16 v[96:99], v[156:159], v[186:189], v[96:99]
	v_mfma_f32_16x16x32_bf16 v[84:87], v[148:151], v[194:197], v[84:87]
	v_mfma_f32_16x16x32_bf16 v[80:83], v[156:159], v[194:197], v[80:83]
	v_mfma_f32_16x16x32_bf16 v[68:71], v[148:151], v[202:205], v[68:71]
	v_mfma_f32_16x16x32_bf16 v[64:67], v[156:159], v[202:205], v[64:67]
	v_mfma_f32_16x16x32_bf16 v[116:119], v[152:155], v[182:185], v[116:119]
	v_mfma_f32_16x16x32_bf16 v[112:115], v[160:163], v[182:185], v[112:115]
	v_mfma_f32_16x16x32_bf16 v[100:103], v[152:155], v[190:193], v[100:103]
	v_mfma_f32_16x16x32_bf16 v[96:99], v[160:163], v[190:193], v[96:99]
	v_mfma_f32_16x16x32_bf16 v[84:87], v[152:155], v[198:201], v[84:87]
	v_mfma_f32_16x16x32_bf16 v[80:83], v[160:163], v[198:201], v[80:83]
	v_mfma_f32_16x16x32_bf16 v[68:71], v[152:155], v[206:209], v[68:71]
	v_mfma_f32_16x16x32_bf16 v[64:67], v[160:163], v[206:209], v[64:67]
	s_setprio 0
	s_barrier
; #define PG8_STAGE(bufoff, gbase, voff) do { _Pragma("unroll") for (int _i = 0; _i < 2; ++_i) \
;         __builtin_amdgcn_global_load_lds((const unsigned*)((const char*)(gbase) + (voff)[_i]), (LAS unsigned*)(lds + (bufoff) + ldsw + _i * 8192), 16, 0, 0); } while (0)
; #define PG8_LDA(dst, b, h) do { _Pragma("unroll") for (int m = 0; m < 4; ++m) _Pragma("unroll") for (int k = 0; k < 2; ++k) dst[m][k] = *(const LAS bf16x8*)(lds + PG8_SA(b, h) + aoff + m * 2048 + k * 1024); } while (0)
; #define PG8_MMA(ai, bj, At, Bt) do { __builtin_amdgcn_s_setprio(1); _Pragma("unroll") for (int m = 0; m < 4; ++m) _Pragma("unroll") for (int n = 0; n < 2; ++n) _Pragma("unroll") for (int k = 0; k < 2; ++k) \
;         acc[ai][bj][m][n] = __builtin_amdgcn_mfma_f32_16x16x32_bf16(Bt[n][k], At[m][k], acc[ai][bj][m][n], 0, 0, 0); __builtin_amdgcn_s_setprio(0); } while (0)
; #define PG8_WAIT_V(n) asm volatile("s_waitcnt vmcnt(" #n ")" ::: "memory")
; #define PG8_WAIT_L(n) asm volatile("s_waitcnt lgkmcnt(" #n ")" ::: "memory")
; #define PG8_BAR __builtin_amdgcn_s_barrier()
; #define PG8_SCHED __builtin_amdgcn_sched_barrier(0)
; template <class Epi, class Sched, bool ALIGN_EPI>
; DI void gemm_phase(LAS unsigned char* lds, const Gemm g, const Sched& S, const Epi& E) {
;     ...
;             PG8_LDA(At, 1, 1); PG8_STAGE(PG8_SB(1, 0), b3, voffA); PG8_STAGE(PG8_SB(1, 1), b3 + hstep, voffA); PG8_STAGE(PG8_SA(1, 0), a3, voffA);
;             PG8_WAIT_V(8); PG8_WAIT_L(0); PG8_BAR; PG8_MMA(1, 0, At, B0); PG8_MMA(1, 1, At, B1); PG8_BAR; PG8_SCHED;
;         }
;         if constexpr (ALIGN_EPI) { if (wr == 0) PG8_BAR; }
	s_add_i32 s18, s43, s20
	s_mov_b32 m0, s18
	ds_read_b128 v[164:167], v135 offset:49152
	ds_read_b128 v[182:185], v135 offset:50176
	ds_read_b128 v[186:189], v135 offset:51200
	ds_read_b128 v[190:193], v135 offset:52224
	ds_read_b128 v[194:197], v135 offset:53248
	ds_read_b128 v[198:201], v135 offset:54272
	ds_read_b128 v[202:205], v135 offset:55296
	ds_read_b128 v[206:209], v135 offset:56320
	global_load_lds_dwordx4 v174, s[94:95]
	s_add_i32 m0, s18, 0x2000
	s_add_u32 s16, s16, 0x40080
	s_addc_u32 s17, s17, 0
	s_add_i32 s18, s48, s20
	global_load_lds_dwordx4 v176, s[94:95]
	s_mov_b32 m0, s18
	s_nop 0
	global_load_lds_dwordx4 v174, s[16:17]
	s_add_i32 m0, s18, 0x2000
	s_nop 0
	global_load_lds_dwordx4 v176, s[16:17]
	s_mov_b32 m0, s26
	s_nop 0
	global_load_lds_dwordx4 v174, s[96:97]
	s_mov_b32 m0, s27
	s_nop 0
	global_load_lds_dwordx4 v176, s[96:97]
	s_waitcnt vmcnt(8)
	s_waitcnt lgkmcnt(0)
	s_barrier
	s_setprio 1
	s_waitcnt lgkmcnt(0)
	v_mfma_f32_16x16x32_bf16 v[60:63], v[128:131], v[164:167], v[60:63]
	v_mfma_f32_16x16x32_bf16 v[56:59], v[140:143], v[164:167], v[56:59]
	v_mfma_f32_16x16x32_bf16 v[44:47], v[128:131], v[186:189], v[44:47]
	v_mfma_f32_16x16x32_bf16 v[40:43], v[140:143], v[186:189], v[40:43]
	v_mfma_f32_16x16x32_bf16 v[28:31], v[128:131], v[194:197], v[28:31]
	v_mfma_f32_16x16x32_bf16 v[24:27], v[140:143], v[194:197], v[24:27]
	v_mfma_f32_16x16x32_bf16 v[12:15], v[128:131], v[202:205], v[12:15]
	v_mfma_f32_16x16x32_bf16 v[8:11], v[140:143], v[202:205], v[8:11]
	v_mfma_f32_16x16x32_bf16 v[60:63], v[136:139], v[182:185], v[60:63]
	v_mfma_f32_16x16x32_bf16 v[56:59], v[144:147], v[182:185], v[56:59]
	v_mfma_f32_16x16x32_bf16 v[44:47], v[136:139], v[190:193], v[44:47]
	v_mfma_f32_16x16x32_bf16 v[40:43], v[144:147], v[190:193], v[40:43]
	v_mfma_f32_16x16x32_bf16 v[28:31], v[136:139], v[198:201], v[28:31]
	v_mfma_f32_16x16x32_bf16 v[24:27], v[144:147], v[198:201], v[24:27]
	v_mfma_f32_16x16x32_bf16 v[12:15], v[136:139], v[206:209], v[12:15]
	v_mfma_f32_16x16x32_bf16 v[8:11], v[144:147], v[206:209], v[8:11]
	s_setprio 0
	s_setprio 1
	v_mfma_f32_16x16x32_bf16 v[52:55], v[148:151], v[164:167], v[52:55]
	v_mfma_f32_16x16x32_bf16 v[48:51], v[156:159], v[164:167], v[48:51]
	v_mfma_f32_16x16x32_bf16 v[36:39], v[148:151], v[186:189], v[36:39]
	v_mfma_f32_16x16x32_bf16 v[32:35], v[156:159], v[186:189], v[32:35]
	v_mfma_f32_16x16x32_bf16 v[20:23], v[148:151], v[194:197], v[20:23]
	v_mfma_f32_16x16x32_bf16 v[16:19], v[156:159], v[194:197], v[16:19]
	v_mfma_f32_16x16x32_bf16 v[4:7], v[148:151], v[202:205], v[4:7]
	v_mfma_f32_16x16x32_bf16 v[0:3], v[156:159], v[202:205], v[0:3]
	v_mfma_f32_16x16x32_bf16 v[52:55], v[152:155], v[182:185], v[52:55]
	v_mfma_f32_16x16x32_bf16 v[48:51], v[160:163], v[182:185], v[48:51]
	v_mfma_f32_16x16x32_bf16 v[36:39], v[152:155], v[190:193], v[36:39]
	v_mfma_f32_16x16x32_bf16 v[32:35], v[160:163], v[190:193], v[32:35]
	v_mfma_f32_16x16x32_bf16 v[20:23], v[152:155], v[198:201], v[20:23]
	v_mfma_f32_16x16x32_bf16 v[16:19], v[160:163], v[198:201], v[16:19]
	v_mfma_f32_16x16x32_bf16 v[4:7], v[152:155], v[206:209], v[4:7]
	v_mfma_f32_16x16x32_bf16 v[0:3], v[160:163], v[206:209], v[0:3]
	s_setprio 0
	s_barrier
	s_add_i32 s42, s42, 2
	s_add_u32 s0, s0, 0x100
	s_addc_u32 s1, s1, 0
	s_add_u32 s36, s36, 0x100
	s_addc_u32 s37, s37, 0
	s_cmp_gt_u32 s42, 13
	s_cbranch_scc0 .LBB0_957
	s_and_b64 vcc, exec, s[12:13]
	s_cbranch_vccz .LBB0_960
	s_barrier
